# ln1/ln2 (ln_rows_b): 96 serialized ds_bpermute wsum steps replaced by DPP reductions + readlane broadcast
# speedup vs baseline: 1.0064x; 1.0064x over previous
; DI unsigned pack2(float a, float b) { const f32x2 v = {a, b}; return __builtin_bit_cast(unsigned, __builtin_convertvector(v, bf16v2)); }
; DI float wsum(float v) { for (int o = 32; o; o >>= 1) v += __shfl_xor(v, o); return v; }
; DI void ln_rows_b(const u16* __restrict__ Zb, const float* __restrict__ g, const float* __restrict__ bta, u16* __restrict__ H) {
;     ...
;     for (int j = 0; j < 4; ++j) {
;       const int row = row0 + j * stride;
;       if (row < T_TOK) {
;         float v[16];
;         unpack8(r[j][0], v); unpack8(r[j][1], v + 8);
;         float s = 0.f;
; #pragma unroll
;         for (int i = 0; i < 16; ++i) s += v[i];
;         const float mu = wsum(s) * (1.f / 1024.f);
;         float q = 0.f;
; #pragma unroll
;         for (int i = 0; i < 16; ++i) { float a = v[i] - mu; q += a * a; }
;         const float rstd = rsqrtf(wsum(q) * (1.f / 1024.f) + LN_EPS);
;         uint4 o0, o1;
;         o0.x = pack2((v[0] - mu) * rstd * gg[0] + bb[0], (v[1] - mu) * rstd * gg[1] + bb[1]); o0.y = pack2((v[2] - mu) * rstd * gg[2] + bb[2], (v[3] - mu) * rstd * gg[3] + bb[3]);
;         o0.z = pack2((v[4] - mu) * rstd * gg[4] + bb[4], (v[5] - mu) * rstd * gg[5] + bb[5]); o0.w = pack2((v[6] - mu) * rstd * gg[6] + bb[6], (v[7] - mu) * rstd * gg[7] + bb[7]);
;         o1.x = pack2((v[8] - mu) * rstd * gg[8] + bb[8], (v[9] - mu) * rstd * gg[9] + bb[9]); o1.y = pack2((v[10] - mu) * rstd * gg[10] + bb[10], (v[11] - mu) * rstd * gg[11] + bb[11]);
;         o1.z = pack2((v[12] - mu) * rstd * gg[12] + bb[12], (v[13] - mu) * rstd * gg[13] + bb[13]); o1.w = pack2((v[14] - mu) * rstd * gg[14] + bb[14], (v[15] - mu) * rstd * gg[15] + bb[15]);
;         *(uint4*)(H + (size_t)row * 1024 + lane * 16) = o0;
;         *(uint4*)(H + (size_t)row * 1024 + lane * 16 + 8) = o1;
.LBB0_765:
	s_or_b64 exec, exec, s[8:9]
	s_waitcnt vmcnt(0)
	v_lshlrev_b32_e32 v84, 16, v60
	v_and_b32_e32 v85, 0xffff0000, v60
	v_add_f32_e32 v83, 0, v84
	v_lshlrev_b32_e32 v60, 16, v61
	v_add_f32_e32 v83, v83, v85
	v_and_b32_e32 v61, 0xffff0000, v61
	v_add_f32_e32 v83, v83, v60
	v_lshlrev_b32_e32 v86, 16, v62
	v_add_f32_e32 v83, v83, v61
	v_and_b32_e32 v87, 0xffff0000, v62
	v_add_f32_e32 v83, v83, v86
	v_lshlrev_b32_e32 v62, 16, v63
	v_add_f32_e32 v83, v83, v87
	v_and_b32_e32 v63, 0xffff0000, v63
	v_add_f32_e32 v83, v83, v62
	v_lshlrev_b32_e32 v88, 16, v56
	v_add_f32_e32 v83, v83, v63
	v_and_b32_e32 v89, 0xffff0000, v56
	v_add_f32_e32 v83, v83, v88
	v_lshlrev_b32_e32 v56, 16, v57
	v_add_f32_e32 v83, v83, v89
	v_and_b32_e32 v57, 0xffff0000, v57
	v_add_f32_e32 v83, v83, v56
	v_lshlrev_b32_e32 v90, 16, v58
	v_add_f32_e32 v83, v83, v57
	v_and_b32_e32 v91, 0xffff0000, v58
	v_add_f32_e32 v83, v83, v90
	v_lshlrev_b32_e32 v58, 16, v59
	v_add_f32_e32 v83, v83, v91
	v_and_b32_e32 v59, 0xffff0000, v59
	v_add_f32_e32 v83, v83, v58
	v_add_f32_e32 v83, v83, v59
	v_lshl_add_u64 v[74:75], v[66:67], 0, v[74:75]
	s_nop 1
	v_add_f32_dpp v83, v83, v83 row_shr:1 row_mask:0xf bank_mask:0xf
	s_nop 1
	v_add_f32_dpp v83, v83, v83 row_shr:2 row_mask:0xf bank_mask:0xf
	s_nop 1
	v_add_f32_dpp v83, v83, v83 row_shr:4 row_mask:0xf bank_mask:0xf
	s_nop 1
	v_add_f32_dpp v83, v83, v83 row_shr:8 row_mask:0xf bank_mask:0xf
	s_nop 1
	v_add_f32_dpp v83, v83, v83 row_bcast:15 row_mask:0xa bank_mask:0xf
	s_nop 1
	v_add_f32_dpp v83, v83, v83 row_bcast:31 row_mask:0xc bank_mask:0xf
	s_nop 0
	v_readlane_b32 s32, v83, 63
	s_nop 1
	v_mov_b32_e32 v83, s32
	v_mul_f32_e32 v92, 0x3a800000, v83
	v_pk_add_f32 v[84:85], v[84:85], v[92:93] op_sel_hi:[1,0] neg_lo:[0,1] neg_hi:[0,1]
	v_pk_add_f32 v[60:61], v[60:61], v[92:93] op_sel_hi:[1,0] neg_lo:[0,1] neg_hi:[0,1]
	v_pk_mul_f32 v[94:95], v[84:85], v[84:85]
	v_pk_mul_f32 v[96:97], v[60:61], v[60:61]
	v_add_f32_e32 v83, v94, v95
	v_pk_add_f32 v[86:87], v[86:87], v[92:93] op_sel_hi:[1,0] neg_lo:[0,1] neg_hi:[0,1]
	v_add_f32_e32 v83, v96, v83
	v_pk_mul_f32 v[98:99], v[86:87], v[86:87]
	v_add_f32_e32 v83, v97, v83
	v_pk_add_f32 v[62:63], v[62:63], v[92:93] op_sel_hi:[1,0] neg_lo:[0,1] neg_hi:[0,1]
	v_add_f32_e32 v83, v98, v83
	v_pk_mul_f32 v[100:101], v[62:63], v[62:63]
	v_add_f32_e32 v83, v99, v83
	v_pk_add_f32 v[88:89], v[88:89], v[92:93] op_sel_hi:[1,0] neg_lo:[0,1] neg_hi:[0,1]
	v_add_f32_e32 v83, v100, v83
	v_pk_mul_f32 v[102:103], v[88:89], v[88:89]
	v_add_f32_e32 v83, v101, v83
	v_pk_add_f32 v[56:57], v[56:57], v[92:93] op_sel_hi:[1,0] neg_lo:[0,1] neg_hi:[0,1]
	v_add_f32_e32 v83, v102, v83
	v_pk_mul_f32 v[104:105], v[56:57], v[56:57]
	v_add_f32_e32 v83, v103, v83
	v_pk_add_f32 v[90:91], v[90:91], v[92:93] op_sel_hi:[1,0] neg_lo:[0,1] neg_hi:[0,1]
	v_add_f32_e32 v83, v104, v83
	v_pk_mul_f32 v[106:107], v[90:91], v[90:91]
	v_add_f32_e32 v83, v105, v83
	v_pk_add_f32 v[58:59], v[58:59], v[92:93] op_sel_hi:[1,0] neg_lo:[0,1] neg_hi:[0,1]
	v_add_f32_e32 v83, v106, v83
	v_pk_mul_f32 v[92:93], v[58:59], v[58:59]
	v_add_f32_e32 v83, v107, v83
	v_add_f32_e32 v83, v92, v83
	v_add_f32_e32 v83, v93, v83
	s_nop 1
	v_add_f32_dpp v83, v83, v83 row_shr:1 row_mask:0xf bank_mask:0xf
	s_nop 1
	v_add_f32_dpp v83, v83, v83 row_shr:2 row_mask:0xf bank_mask:0xf
	s_nop 1
	v_add_f32_dpp v83, v83, v83 row_shr:4 row_mask:0xf bank_mask:0xf
	s_nop 1
	v_add_f32_dpp v83, v83, v83 row_shr:8 row_mask:0xf bank_mask:0xf
	s_nop 1
	v_add_f32_dpp v83, v83, v83 row_bcast:15 row_mask:0xa bank_mask:0xf
	s_nop 1
	v_add_f32_dpp v83, v83, v83 row_bcast:31 row_mask:0xc bank_mask:0xf
	s_nop 0
	v_readlane_b32 s32, v83, 63
	s_nop 1
	v_mov_b32_e32 v83, s32
	v_fmamk_f32 v83, v83, 0x3a800000, v82
	v_mul_f32_e32 v92, 0x4b800000, v83
	v_cmp_gt_f32_e64 s[8:9], s12, v83
	s_nop 1
	v_cndmask_b32_e64 v83, v83, v92, s[8:9]
	v_rsq_f32_e32 v83, v83
	s_nop 0
	v_mul_f32_e32 v92, 0x45800000, v83
	v_cndmask_b32_e64 v92, v83, v92, s[8:9]
	v_pk_mul_f32 v[84:85], v[84:85], v[92:93] op_sel_hi:[1,0]
	v_pk_mul_f32 v[60:61], v[60:61], v[92:93] op_sel_hi:[1,0]
	v_pk_mul_f32 v[86:87], v[86:87], v[92:93] op_sel_hi:[1,0]
	v_pk_mul_f32 v[62:63], v[62:63], v[92:93] op_sel_hi:[1,0]
	v_pk_mul_f32 v[88:89], v[88:89], v[92:93] op_sel_hi:[1,0]
	v_pk_mul_f32 v[56:57], v[56:57], v[92:93] op_sel_hi:[1,0]
	v_pk_mul_f32 v[90:91], v[90:91], v[92:93] op_sel_hi:[1,0]
	v_pk_mul_f32 v[58:59], v[58:59], v[92:93] op_sel_hi:[1,0]
	v_pk_fma_f32 v[84:85], v[24:25], v[84:85], v[28:29]
	v_pk_fma_f32 v[60:61], v[26:27], v[60:61], v[30:31]
	v_pk_fma_f32 v[86:87], v[16:17], v[86:87], v[20:21]
	v_pk_fma_f32 v[62:63], v[18:19], v[62:63], v[22:23]
	v_pk_fma_f32 v[88:89], v[8:9], v[88:89], v[12:13]
	v_pk_fma_f32 v[92:93], v[10:11], v[56:57], v[14:15]
	v_pk_fma_f32 v[90:91], v[0:1], v[90:91], v[4:5]
	v_pk_fma_f32 v[94:95], v[2:3], v[58:59], v[6:7]
	v_cvt_pk_bf16_f32 v56, v84, v85
	v_cvt_pk_bf16_f32 v57, v60, v61
	v_cvt_pk_bf16_f32 v58, v86, v87
	v_cvt_pk_bf16_f32 v59, v62, v63
	v_cvt_pk_bf16_f32 v60, v88, v89
	v_cvt_pk_bf16_f32 v61, v92, v93
	v_cvt_pk_bf16_f32 v62, v90, v91
	v_cvt_pk_bf16_f32 v63, v94, v95
	global_store_dwordx4 v[74:75], v[56:59], off
	global_store_dwordx4 v[74:75], v[60:63], off offset:16
	s_and_saveexec_b64 s[8:9], s[4:5]
	s_cbranch_execnz .LBB0_768
	s_or_b64 exec, exec, s[8:9]
	s_and_saveexec_b64 s[4:5], s[0:1]
	s_cbranch_execnz .LBB0_769

; DI unsigned pack2(float a, float b) { const f32x2 v = {a, b}; return __builtin_bit_cast(unsigned, __builtin_convertvector(v, bf16v2)); }
; DI float wsum(float v) { for (int o = 32; o; o >>= 1) v += __shfl_xor(v, o); return v; }
; DI void ln_rows_b(const u16* __restrict__ Zb, const float* __restrict__ g, const float* __restrict__ bta, u16* __restrict__ H) {
;     ...
;     for (int j = 0; j < 4; ++j) {
;       const int row = row0 + j * stride;
;       if (row < T_TOK) {
;         float v[16];
;         unpack8(r[j][0], v); unpack8(r[j][1], v + 8);
;         float s = 0.f;
; #pragma unroll
;         for (int i = 0; i < 16; ++i) s += v[i];
;         const float mu = wsum(s) * (1.f / 1024.f);
;         float q = 0.f;
; #pragma unroll
;         for (int i = 0; i < 16; ++i) { float a = v[i] - mu; q += a * a; }
;         const float rstd = rsqrtf(wsum(q) * (1.f / 1024.f) + LN_EPS);
;         uint4 o0, o1;
;         o0.x = pack2((v[0] - mu) * rstd * gg[0] + bb[0], (v[1] - mu) * rstd * gg[1] + bb[1]); o0.y = pack2((v[2] - mu) * rstd * gg[2] + bb[2], (v[3] - mu) * rstd * gg[3] + bb[3]);
;         o0.z = pack2((v[4] - mu) * rstd * gg[4] + bb[4], (v[5] - mu) * rstd * gg[5] + bb[5]); o0.w = pack2((v[6] - mu) * rstd * gg[6] + bb[6], (v[7] - mu) * rstd * gg[7] + bb[7]);
;         o1.x = pack2((v[8] - mu) * rstd * gg[8] + bb[8], (v[9] - mu) * rstd * gg[9] + bb[9]); o1.y = pack2((v[10] - mu) * rstd * gg[10] + bb[10], (v[11] - mu) * rstd * gg[11] + bb[11]);
;         o1.z = pack2((v[12] - mu) * rstd * gg[12] + bb[12], (v[13] - mu) * rstd * gg[13] + bb[13]); o1.w = pack2((v[14] - mu) * rstd * gg[14] + bb[14], (v[15] - mu) * rstd * gg[15] + bb[15]);
;         *(uint4*)(H + (size_t)row * 1024 + lane * 16) = o0;
;         *(uint4*)(H + (size_t)row * 1024 + lane * 16 + 8) = o1;
.LBB0_768:
	v_lshlrev_b32_e32 v56, 16, v52
	v_and_b32_e32 v57, 0xffff0000, v52
	v_add_f32_e32 v83, 0, v56
	v_lshlrev_b32_e32 v58, 16, v53
	v_add_f32_e32 v83, v83, v57
	v_and_b32_e32 v59, 0xffff0000, v53
	v_add_f32_e32 v83, v83, v58
	v_lshlrev_b32_e32 v60, 16, v54
	v_add_f32_e32 v83, v83, v59
	v_and_b32_e32 v61, 0xffff0000, v54
	v_add_f32_e32 v83, v83, v60
	v_lshlrev_b32_e32 v62, 16, v55
	v_add_f32_e32 v83, v83, v61
	v_and_b32_e32 v63, 0xffff0000, v55
	v_add_f32_e32 v83, v83, v62
	v_lshlrev_b32_e32 v74, 16, v48
	v_add_f32_e32 v83, v83, v63
	v_and_b32_e32 v75, 0xffff0000, v48
	v_add_f32_e32 v83, v83, v74
	v_lshlrev_b32_e32 v84, 16, v49
	v_add_f32_e32 v83, v83, v75
	v_and_b32_e32 v85, 0xffff0000, v49
	v_add_f32_e32 v83, v83, v84
	v_lshlrev_b32_e32 v86, 16, v50
	v_add_f32_e32 v83, v83, v85
	v_and_b32_e32 v87, 0xffff0000, v50
	v_add_f32_e32 v83, v83, v86
	v_lshlrev_b32_e32 v88, 16, v51
	v_add_f32_e32 v83, v83, v87
	v_and_b32_e32 v89, 0xffff0000, v51
	v_add_f32_e32 v83, v83, v88
	v_add_f32_e32 v83, v83, v89
	s_nop 1
	v_add_f32_dpp v83, v83, v83 row_shr:1 row_mask:0xf bank_mask:0xf
	s_nop 1
	v_add_f32_dpp v83, v83, v83 row_shr:2 row_mask:0xf bank_mask:0xf
	s_nop 1
	v_add_f32_dpp v83, v83, v83 row_shr:4 row_mask:0xf bank_mask:0xf
	s_nop 1
	v_add_f32_dpp v83, v83, v83 row_shr:8 row_mask:0xf bank_mask:0xf
	s_nop 1
	v_add_f32_dpp v83, v83, v83 row_bcast:15 row_mask:0xa bank_mask:0xf
	s_nop 1
	v_add_f32_dpp v83, v83, v83 row_bcast:31 row_mask:0xc bank_mask:0xf
	s_nop 0
	v_readlane_b32 s32, v83, 63
	s_nop 1
	v_mov_b32_e32 v83, s32
	v_mul_f32_e32 v90, 0x3a800000, v83
	v_pk_add_f32 v[56:57], v[56:57], v[90:91] op_sel_hi:[1,0] neg_lo:[0,1] neg_hi:[0,1]
	v_pk_add_f32 v[58:59], v[58:59], v[90:91] op_sel_hi:[1,0] neg_lo:[0,1] neg_hi:[0,1]
	v_pk_mul_f32 v[92:93], v[56:57], v[56:57]
	v_pk_mul_f32 v[94:95], v[58:59], v[58:59]
	v_add_f32_e32 v83, v92, v93
	v_pk_add_f32 v[60:61], v[60:61], v[90:91] op_sel_hi:[1,0] neg_lo:[0,1] neg_hi:[0,1]
	v_add_f32_e32 v83, v94, v83
	v_pk_mul_f32 v[96:97], v[60:61], v[60:61]
	v_add_f32_e32 v83, v95, v83
	v_pk_add_f32 v[62:63], v[62:63], v[90:91] op_sel_hi:[1,0] neg_lo:[0,1] neg_hi:[0,1]
	v_add_f32_e32 v83, v96, v83
	v_pk_mul_f32 v[98:99], v[62:63], v[62:63]
	v_add_f32_e32 v83, v97, v83
	v_pk_add_f32 v[74:75], v[74:75], v[90:91] op_sel_hi:[1,0] neg_lo:[0,1] neg_hi:[0,1]
	v_add_f32_e32 v83, v98, v83
	v_pk_mul_f32 v[100:101], v[74:75], v[74:75]
	v_add_f32_e32 v83, v99, v83
	v_pk_add_f32 v[84:85], v[84:85], v[90:91] op_sel_hi:[1,0] neg_lo:[0,1] neg_hi:[0,1]
	v_add_f32_e32 v83, v100, v83
	v_pk_mul_f32 v[102:103], v[84:85], v[84:85]
	v_add_f32_e32 v83, v101, v83
	v_pk_add_f32 v[86:87], v[86:87], v[90:91] op_sel_hi:[1,0] neg_lo:[0,1] neg_hi:[0,1]
	v_add_f32_e32 v83, v102, v83
	v_pk_mul_f32 v[104:105], v[86:87], v[86:87]
	v_add_f32_e32 v83, v103, v83
	v_pk_add_f32 v[88:89], v[88:89], v[90:91] op_sel_hi:[1,0] neg_lo:[0,1] neg_hi:[0,1]
	v_add_f32_e32 v83, v104, v83
	v_pk_mul_f32 v[90:91], v[88:89], v[88:89]
	v_add_f32_e32 v83, v105, v83
	v_add_f32_e32 v83, v90, v83
	v_add_f32_e32 v83, v91, v83
	s_nop 1
	v_add_f32_dpp v83, v83, v83 row_shr:1 row_mask:0xf bank_mask:0xf
	s_nop 1
	v_add_f32_dpp v83, v83, v83 row_shr:2 row_mask:0xf bank_mask:0xf
	s_nop 1
	v_add_f32_dpp v83, v83, v83 row_shr:4 row_mask:0xf bank_mask:0xf
	s_nop 1
	v_add_f32_dpp v83, v83, v83 row_shr:8 row_mask:0xf bank_mask:0xf
	s_nop 1
	v_add_f32_dpp v83, v83, v83 row_bcast:15 row_mask:0xa bank_mask:0xf
	s_nop 1
	v_add_f32_dpp v83, v83, v83 row_bcast:31 row_mask:0xc bank_mask:0xf
	s_nop 0
	v_readlane_b32 s32, v83, 63
	s_nop 1
	v_mov_b32_e32 v83, s32
	v_fmamk_f32 v83, v83, 0x3a800000, v82
	v_mul_f32_e32 v90, 0x4b800000, v83
	v_cmp_gt_f32_e64 s[4:5], s12, v83
	s_nop 1
	v_cndmask_b32_e64 v83, v83, v90, s[4:5]
	v_rsq_f32_e32 v83, v83
	s_nop 0
	v_mul_f32_e32 v90, 0x45800000, v83
	v_cndmask_b32_e64 v90, v83, v90, s[4:5]
	v_pk_mul_f32 v[56:57], v[56:57], v[90:91] op_sel_hi:[1,0]
	v_pk_mul_f32 v[58:59], v[58:59], v[90:91] op_sel_hi:[1,0]
	v_pk_mul_f32 v[60:61], v[60:61], v[90:91] op_sel_hi:[1,0]
	v_pk_mul_f32 v[74:75], v[74:75], v[90:91] op_sel_hi:[1,0]
	v_pk_mul_f32 v[62:63], v[62:63], v[90:91] op_sel_hi:[1,0]
	v_pk_fma_f32 v[56:57], v[24:25], v[56:57], v[28:29]
	v_pk_fma_f32 v[58:59], v[26:27], v[58:59], v[30:31]
	v_pk_fma_f32 v[60:61], v[16:17], v[60:61], v[20:21]
	v_pk_fma_f32 v[74:75], v[8:9], v[74:75], v[12:13]
	v_pk_mul_f32 v[84:85], v[84:85], v[90:91] op_sel_hi:[1,0]
	v_pk_mul_f32 v[86:87], v[86:87], v[90:91] op_sel_hi:[1,0]
	v_pk_mul_f32 v[88:89], v[88:89], v[90:91] op_sel_hi:[1,0]
	v_pk_fma_f32 v[62:63], v[18:19], v[62:63], v[22:23]
	v_cvt_pk_bf16_f32 v56, v56, v57
	v_cvt_pk_bf16_f32 v57, v58, v59
	v_cvt_pk_bf16_f32 v58, v60, v61
	v_cvt_pk_bf16_f32 v60, v74, v75
	v_lshlrev_b64 v[74:75], 11, v[68:69]
	v_pk_fma_f32 v[84:85], v[10:11], v[84:85], v[14:15]
	v_pk_fma_f32 v[86:87], v[0:1], v[86:87], v[4:5]
	v_pk_fma_f32 v[88:89], v[2:3], v[88:89], v[6:7]
	v_cvt_pk_bf16_f32 v59, v62, v63
	v_lshl_add_u64 v[74:75], v[66:67], 0, v[74:75]
	v_cvt_pk_bf16_f32 v61, v84, v85
	v_cvt_pk_bf16_f32 v62, v86, v87
	v_cvt_pk_bf16_f32 v63, v88, v89
	global_store_dwordx4 v[74:75], v[56:59], off
	global_store_dwordx4 v[74:75], v[60:63], off offset:16
	s_or_b64 exec, exec, s[8:9]
	s_and_saveexec_b64 s[4:5], s[0:1]
	s_cbranch_execz .LBB0_767
; DI unsigned pack2(float a, float b) { const f32x2 v = {a, b}; return __builtin_bit_cast(unsigned, __builtin_convertvector(v, bf16v2)); }
; DI float wsum(float v) { for (int o = 32; o; o >>= 1) v += __shfl_xor(v, o); return v; }
; DI void ln_rows_b(const u16* __restrict__ Zb, const float* __restrict__ g, const float* __restrict__ bta, u16* __restrict__ H) {
;     ...
;     for (int j = 0; j < 4; ++j) {
;       const int row = row0 + j * stride;
;       if (row < T_TOK) {
;         float v[16];
;         unpack8(r[j][0], v); unpack8(r[j][1], v + 8);
;         float s = 0.f;
; #pragma unroll
;         for (int i = 0; i < 16; ++i) s += v[i];
;         const float mu = wsum(s) * (1.f / 1024.f);
;         float q = 0.f;
; #pragma unroll
;         for (int i = 0; i < 16; ++i) { float a = v[i] - mu; q += a * a; }
;         const float rstd = rsqrtf(wsum(q) * (1.f / 1024.f) + LN_EPS);
;         uint4 o0, o1;
;         o0.x = pack2((v[0] - mu) * rstd * gg[0] + bb[0], (v[1] - mu) * rstd * gg[1] + bb[1]); o0.y = pack2((v[2] - mu) * rstd * gg[2] + bb[2], (v[3] - mu) * rstd * gg[3] + bb[3]);
;         o0.z = pack2((v[4] - mu) * rstd * gg[4] + bb[4], (v[5] - mu) * rstd * gg[5] + bb[5]); o0.w = pack2((v[6] - mu) * rstd * gg[6] + bb[6], (v[7] - mu) * rstd * gg[7] + bb[7]);
;         o1.x = pack2((v[8] - mu) * rstd * gg[8] + bb[8], (v[9] - mu) * rstd * gg[9] + bb[9]); o1.y = pack2((v[10] - mu) * rstd * gg[10] + bb[10], (v[11] - mu) * rstd * gg[11] + bb[11]);
;         o1.z = pack2((v[12] - mu) * rstd * gg[12] + bb[12], (v[13] - mu) * rstd * gg[13] + bb[13]); o1.w = pack2((v[14] - mu) * rstd * gg[14] + bb[14], (v[15] - mu) * rstd * gg[15] + bb[15]);
;         *(uint4*)(H + (size_t)row * 1024 + lane * 16) = o0;
;         *(uint4*)(H + (size_t)row * 1024 + lane * 16 + 8) = o1;
.LBB0_769:
	v_lshlrev_b32_e32 v56, 16, v44
	v_and_b32_e32 v57, 0xffff0000, v44
	v_add_f32_e32 v69, 0, v56
	v_lshlrev_b32_e32 v58, 16, v45
	v_add_f32_e32 v69, v69, v57
	v_and_b32_e32 v59, 0xffff0000, v45
	v_add_f32_e32 v69, v69, v58
	v_lshlrev_b32_e32 v60, 16, v46
	v_add_f32_e32 v69, v69, v59
	v_and_b32_e32 v61, 0xffff0000, v46
	v_add_f32_e32 v69, v69, v60
	v_lshlrev_b32_e32 v62, 16, v47
	v_add_f32_e32 v69, v69, v61
	v_and_b32_e32 v63, 0xffff0000, v47
	v_add_f32_e32 v69, v69, v62
	v_lshlrev_b32_e32 v74, 16, v40
	v_add_f32_e32 v69, v69, v63
	v_and_b32_e32 v75, 0xffff0000, v40
	v_add_f32_e32 v69, v69, v74
	v_lshlrev_b32_e32 v84, 16, v41
	v_add_f32_e32 v69, v69, v75
	v_and_b32_e32 v85, 0xffff0000, v41
	v_add_f32_e32 v69, v69, v84
	v_lshlrev_b32_e32 v86, 16, v42
	v_add_f32_e32 v69, v69, v85
	v_and_b32_e32 v87, 0xffff0000, v42
	v_add_f32_e32 v69, v69, v86
	v_lshlrev_b32_e32 v88, 16, v43
	v_add_f32_e32 v69, v69, v87
	v_and_b32_e32 v89, 0xffff0000, v43
	v_add_f32_e32 v69, v69, v88
	v_add_f32_e32 v69, v69, v89
	v_lshlrev_b64 v[72:73], 11, v[72:73]
	v_lshl_add_u64 v[72:73], v[66:67], 0, v[72:73]
	s_nop 1
	v_add_f32_dpp v69, v69, v69 row_shr:1 row_mask:0xf bank_mask:0xf
	s_nop 1
	v_add_f32_dpp v69, v69, v69 row_shr:2 row_mask:0xf bank_mask:0xf
	s_nop 1
	v_add_f32_dpp v69, v69, v69 row_shr:4 row_mask:0xf bank_mask:0xf
	s_nop 1
	v_add_f32_dpp v69, v69, v69 row_shr:8 row_mask:0xf bank_mask:0xf
	s_nop 1
	v_add_f32_dpp v69, v69, v69 row_bcast:15 row_mask:0xa bank_mask:0xf
	s_nop 1
	v_add_f32_dpp v69, v69, v69 row_bcast:31 row_mask:0xc bank_mask:0xf
	s_nop 0
	v_readlane_b32 s32, v69, 63
	s_nop 1
	v_mov_b32_e32 v69, s32
	v_mul_f32_e32 v90, 0x3a800000, v69
	v_pk_add_f32 v[56:57], v[56:57], v[90:91] op_sel_hi:[1,0] neg_lo:[0,1] neg_hi:[0,1]
	v_pk_add_f32 v[58:59], v[58:59], v[90:91] op_sel_hi:[1,0] neg_lo:[0,1] neg_hi:[0,1]
	v_pk_mul_f32 v[92:93], v[56:57], v[56:57]
	v_pk_mul_f32 v[94:95], v[58:59], v[58:59]
	v_add_f32_e32 v69, v92, v93
	v_pk_add_f32 v[60:61], v[60:61], v[90:91] op_sel_hi:[1,0] neg_lo:[0,1] neg_hi:[0,1]
	v_add_f32_e32 v69, v94, v69
	v_pk_mul_f32 v[96:97], v[60:61], v[60:61]
	v_add_f32_e32 v69, v95, v69
	v_pk_add_f32 v[62:63], v[62:63], v[90:91] op_sel_hi:[1,0] neg_lo:[0,1] neg_hi:[0,1]
	v_add_f32_e32 v69, v96, v69
	v_pk_mul_f32 v[98:99], v[62:63], v[62:63]
	v_add_f32_e32 v69, v97, v69
	v_pk_add_f32 v[74:75], v[74:75], v[90:91] op_sel_hi:[1,0] neg_lo:[0,1] neg_hi:[0,1]
	v_add_f32_e32 v69, v98, v69
	v_pk_mul_f32 v[100:101], v[74:75], v[74:75]
	v_add_f32_e32 v69, v99, v69
	v_pk_add_f32 v[84:85], v[84:85], v[90:91] op_sel_hi:[1,0] neg_lo:[0,1] neg_hi:[0,1]
	v_add_f32_e32 v69, v100, v69
	v_pk_mul_f32 v[102:103], v[84:85], v[84:85]
	v_add_f32_e32 v69, v101, v69
	v_pk_add_f32 v[86:87], v[86:87], v[90:91] op_sel_hi:[1,0] neg_lo:[0,1] neg_hi:[0,1]
	v_add_f32_e32 v69, v102, v69
	v_pk_mul_f32 v[104:105], v[86:87], v[86:87]
	v_add_f32_e32 v69, v103, v69
	v_pk_add_f32 v[88:89], v[88:89], v[90:91] op_sel_hi:[1,0] neg_lo:[0,1] neg_hi:[0,1]
	v_add_f32_e32 v69, v104, v69
	v_pk_mul_f32 v[90:91], v[88:89], v[88:89]
	v_add_f32_e32 v69, v105, v69
	v_add_f32_e32 v69, v90, v69
	v_add_f32_e32 v69, v91, v69
	s_nop 1
	v_add_f32_dpp v69, v69, v69 row_shr:1 row_mask:0xf bank_mask:0xf
	s_nop 1
	v_add_f32_dpp v69, v69, v69 row_shr:2 row_mask:0xf bank_mask:0xf
	s_nop 1
	v_add_f32_dpp v69, v69, v69 row_shr:4 row_mask:0xf bank_mask:0xf
	s_nop 1
	v_add_f32_dpp v69, v69, v69 row_shr:8 row_mask:0xf bank_mask:0xf
	s_nop 1
	v_add_f32_dpp v69, v69, v69 row_bcast:15 row_mask:0xa bank_mask:0xf
	s_nop 1
	v_add_f32_dpp v69, v69, v69 row_bcast:31 row_mask:0xc bank_mask:0xf
	s_nop 0
	v_readlane_b32 s32, v69, 63
	s_nop 1
	v_mov_b32_e32 v69, s32
	v_fmamk_f32 v69, v69, 0x3a800000, v82
	v_mul_f32_e32 v83, 0x4b800000, v69
	v_cmp_gt_f32_e64 s[0:1], s12, v69
	s_nop 1
	v_cndmask_b32_e64 v69, v69, v83, s[0:1]
	v_rsq_f32_e32 v69, v69
	s_nop 0
	v_mul_f32_e32 v83, 0x45800000, v69
	v_cndmask_b32_e64 v90, v69, v83, s[0:1]
	v_pk_mul_f32 v[56:57], v[56:57], v[90:91] op_sel_hi:[1,0]
	v_pk_mul_f32 v[58:59], v[58:59], v[90:91] op_sel_hi:[1,0]
	v_pk_mul_f32 v[60:61], v[60:61], v[90:91] op_sel_hi:[1,0]
	v_pk_mul_f32 v[62:63], v[62:63], v[90:91] op_sel_hi:[1,0]
	v_pk_mul_f32 v[74:75], v[74:75], v[90:91] op_sel_hi:[1,0]
	v_pk_mul_f32 v[84:85], v[84:85], v[90:91] op_sel_hi:[1,0]
	v_pk_mul_f32 v[86:87], v[86:87], v[90:91] op_sel_hi:[1,0]
	v_pk_mul_f32 v[88:89], v[88:89], v[90:91] op_sel_hi:[1,0]
	v_pk_fma_f32 v[56:57], v[24:25], v[56:57], v[28:29]
	v_pk_fma_f32 v[58:59], v[26:27], v[58:59], v[30:31]
	v_pk_fma_f32 v[60:61], v[16:17], v[60:61], v[20:21]
	v_pk_fma_f32 v[62:63], v[18:19], v[62:63], v[22:23]
	v_pk_fma_f32 v[74:75], v[8:9], v[74:75], v[12:13]
	v_pk_fma_f32 v[84:85], v[10:11], v[84:85], v[14:15]
	v_pk_fma_f32 v[86:87], v[0:1], v[86:87], v[4:5]
	v_pk_fma_f32 v[88:89], v[2:3], v[88:89], v[6:7]
	v_cvt_pk_bf16_f32 v56, v56, v57
	v_cvt_pk_bf16_f32 v57, v58, v59
	v_cvt_pk_bf16_f32 v58, v60, v61
	v_cvt_pk_bf16_f32 v59, v62, v63
	v_cvt_pk_bf16_f32 v60, v74, v75
	v_cvt_pk_bf16_f32 v61, v84, v85
	v_cvt_pk_bf16_f32 v62, v86, v87
	v_cvt_pk_bf16_f32 v63, v88, v89
	global_store_dwordx4 v[72:73], v[56:59], off
	global_store_dwordx4 v[72:73], v[60:63], off offset:16
	s_or_b64 exec, exec, s[4:5]
	s_and_saveexec_b64 s[0:1], vcc
	s_cbranch_execz .LBB0_758
; DI unsigned pack2(float a, float b) { const f32x2 v = {a, b}; return __builtin_bit_cast(unsigned, __builtin_convertvector(v, bf16v2)); }
; DI float wsum(float v) { for (int o = 32; o; o >>= 1) v += __shfl_xor(v, o); return v; }
; DI void ln_rows_b(const u16* __restrict__ Zb, const float* __restrict__ g, const float* __restrict__ bta, u16* __restrict__ H) {
;     ...
;     for (int j = 0; j < 4; ++j) {
;       const int row = row0 + j * stride;
;       if (row < T_TOK) {
;         float v[16];
;         unpack8(r[j][0], v); unpack8(r[j][1], v + 8);
;         float s = 0.f;
; #pragma unroll
;         for (int i = 0; i < 16; ++i) s += v[i];
;         const float mu = wsum(s) * (1.f / 1024.f);
;         float q = 0.f;
; #pragma unroll
;         for (int i = 0; i < 16; ++i) { float a = v[i] - mu; q += a * a; }
;         const float rstd = rsqrtf(wsum(q) * (1.f / 1024.f) + LN_EPS);
;         uint4 o0, o1;
;         o0.x = pack2((v[0] - mu) * rstd * gg[0] + bb[0], (v[1] - mu) * rstd * gg[1] + bb[1]); o0.y = pack2((v[2] - mu) * rstd * gg[2] + bb[2], (v[3] - mu) * rstd * gg[3] + bb[3]);
;         o0.z = pack2((v[4] - mu) * rstd * gg[4] + bb[4], (v[5] - mu) * rstd * gg[5] + bb[5]); o0.w = pack2((v[6] - mu) * rstd * gg[6] + bb[6], (v[7] - mu) * rstd * gg[7] + bb[7]);
;         o1.x = pack2((v[8] - mu) * rstd * gg[8] + bb[8], (v[9] - mu) * rstd * gg[9] + bb[9]); o1.y = pack2((v[10] - mu) * rstd * gg[10] + bb[10], (v[11] - mu) * rstd * gg[11] + bb[11]);
;         o1.z = pack2((v[12] - mu) * rstd * gg[12] + bb[12], (v[13] - mu) * rstd * gg[13] + bb[13]); o1.w = pack2((v[14] - mu) * rstd * gg[14] + bb[14], (v[15] - mu) * rstd * gg[15] + bb[15]);
;         *(uint4*)(H + (size_t)row * 1024 + lane * 16) = o0;
;         *(uint4*)(H + (size_t)row * 1024 + lane * 16 + 8) = o1;
.LBB0_770:
	v_lshlrev_b32_e32 v56, 16, v36
	v_and_b32_e32 v57, 0xffff0000, v36
	v_add_f32_e32 v69, 0, v56
	v_lshlrev_b32_e32 v58, 16, v37
	v_add_f32_e32 v69, v69, v57
	v_and_b32_e32 v59, 0xffff0000, v37
	v_add_f32_e32 v69, v69, v58
	v_lshlrev_b32_e32 v60, 16, v38
	v_add_f32_e32 v69, v69, v59
	v_and_b32_e32 v61, 0xffff0000, v38
	v_add_f32_e32 v69, v69, v60
	v_lshlrev_b32_e32 v62, 16, v39
	v_add_f32_e32 v69, v69, v61
	v_and_b32_e32 v63, 0xffff0000, v39
	v_add_f32_e32 v69, v69, v62
	v_lshlrev_b32_e32 v72, 16, v32
	v_add_f32_e32 v69, v69, v63
	v_and_b32_e32 v73, 0xffff0000, v32
	v_add_f32_e32 v69, v69, v72
	v_lshlrev_b32_e32 v74, 16, v33
	v_add_f32_e32 v69, v69, v73
	v_and_b32_e32 v75, 0xffff0000, v33
	v_add_f32_e32 v69, v69, v74
	v_lshlrev_b32_e32 v84, 16, v34
	v_add_f32_e32 v69, v69, v75
	v_and_b32_e32 v85, 0xffff0000, v34
	v_add_f32_e32 v69, v69, v84
	v_lshlrev_b32_e32 v86, 16, v35
	v_add_f32_e32 v69, v69, v85
	v_and_b32_e32 v87, 0xffff0000, v35
	v_add_f32_e32 v69, v69, v86
	v_add_f32_e32 v69, v69, v87
	v_lshlrev_b64 v[70:71], 11, v[70:71]
	v_lshl_add_u64 v[70:71], v[66:67], 0, v[70:71]
	s_nop 1
	v_add_f32_dpp v69, v69, v69 row_shr:1 row_mask:0xf bank_mask:0xf
	s_nop 1
	v_add_f32_dpp v69, v69, v69 row_shr:2 row_mask:0xf bank_mask:0xf
	s_nop 1
	v_add_f32_dpp v69, v69, v69 row_shr:4 row_mask:0xf bank_mask:0xf
	s_nop 1
	v_add_f32_dpp v69, v69, v69 row_shr:8 row_mask:0xf bank_mask:0xf
	s_nop 1
	v_add_f32_dpp v69, v69, v69 row_bcast:15 row_mask:0xa bank_mask:0xf
	s_nop 1
	v_add_f32_dpp v69, v69, v69 row_bcast:31 row_mask:0xc bank_mask:0xf
	s_nop 0
	v_readlane_b32 s32, v69, 63
	s_nop 1
	v_mov_b32_e32 v69, s32
	v_mul_f32_e32 v88, 0x3a800000, v69
	v_pk_add_f32 v[56:57], v[56:57], v[88:89] op_sel_hi:[1,0] neg_lo:[0,1] neg_hi:[0,1]
	v_pk_add_f32 v[58:59], v[58:59], v[88:89] op_sel_hi:[1,0] neg_lo:[0,1] neg_hi:[0,1]
	v_pk_mul_f32 v[90:91], v[56:57], v[56:57]
	v_pk_mul_f32 v[92:93], v[58:59], v[58:59]
	v_add_f32_e32 v69, v90, v91
	v_pk_add_f32 v[60:61], v[60:61], v[88:89] op_sel_hi:[1,0] neg_lo:[0,1] neg_hi:[0,1]
	v_add_f32_e32 v69, v92, v69
	v_pk_mul_f32 v[94:95], v[60:61], v[60:61]
	v_add_f32_e32 v69, v93, v69
	v_pk_add_f32 v[62:63], v[62:63], v[88:89] op_sel_hi:[1,0] neg_lo:[0,1] neg_hi:[0,1]
	v_add_f32_e32 v69, v94, v69
	v_pk_mul_f32 v[96:97], v[62:63], v[62:63]
	v_add_f32_e32 v69, v95, v69
	v_pk_add_f32 v[72:73], v[72:73], v[88:89] op_sel_hi:[1,0] neg_lo:[0,1] neg_hi:[0,1]
	v_add_f32_e32 v69, v96, v69
	v_pk_mul_f32 v[98:99], v[72:73], v[72:73]
	v_add_f32_e32 v69, v97, v69
	v_pk_add_f32 v[74:75], v[74:75], v[88:89] op_sel_hi:[1,0] neg_lo:[0,1] neg_hi:[0,1]
	v_add_f32_e32 v69, v98, v69
	v_pk_mul_f32 v[100:101], v[74:75], v[74:75]
	v_add_f32_e32 v69, v99, v69
	v_pk_add_f32 v[84:85], v[84:85], v[88:89] op_sel_hi:[1,0] neg_lo:[0,1] neg_hi:[0,1]
	v_add_f32_e32 v69, v100, v69
	v_pk_mul_f32 v[102:103], v[84:85], v[84:85]
	v_add_f32_e32 v69, v101, v69
	v_pk_add_f32 v[86:87], v[86:87], v[88:89] op_sel_hi:[1,0] neg_lo:[0,1] neg_hi:[0,1]
	v_add_f32_e32 v69, v102, v69
	v_pk_mul_f32 v[88:89], v[86:87], v[86:87]
	v_add_f32_e32 v69, v103, v69
	v_add_f32_e32 v69, v88, v69
	v_add_f32_e32 v69, v89, v69
	s_nop 1
	v_add_f32_dpp v69, v69, v69 row_shr:1 row_mask:0xf bank_mask:0xf
	s_nop 1
	v_add_f32_dpp v69, v69, v69 row_shr:2 row_mask:0xf bank_mask:0xf
	s_nop 1
	v_add_f32_dpp v69, v69, v69 row_shr:4 row_mask:0xf bank_mask:0xf
	s_nop 1
	v_add_f32_dpp v69, v69, v69 row_shr:8 row_mask:0xf bank_mask:0xf
	s_nop 1
	v_add_f32_dpp v69, v69, v69 row_bcast:15 row_mask:0xa bank_mask:0xf
	s_nop 1
	v_add_f32_dpp v69, v69, v69 row_bcast:31 row_mask:0xc bank_mask:0xf
	s_nop 0
	v_readlane_b32 s32, v69, 63
	s_nop 1
	v_mov_b32_e32 v69, s32
	v_fmamk_f32 v69, v69, 0x3a800000, v82
	v_mul_f32_e32 v83, 0x4b800000, v69
	v_cmp_gt_f32_e32 vcc, s12, v69
	s_nop 1
	v_cndmask_b32_e32 v69, v69, v83, vcc
	v_rsq_f32_e32 v69, v69
	s_nop 0
	v_mul_f32_e32 v83, 0x45800000, v69
	v_cndmask_b32_e32 v88, v69, v83, vcc
	v_pk_mul_f32 v[56:57], v[56:57], v[88:89] op_sel_hi:[1,0]
	v_pk_mul_f32 v[58:59], v[58:59], v[88:89] op_sel_hi:[1,0]
	v_pk_mul_f32 v[60:61], v[60:61], v[88:89] op_sel_hi:[1,0]
	v_pk_mul_f32 v[62:63], v[62:63], v[88:89] op_sel_hi:[1,0]
	v_pk_mul_f32 v[72:73], v[72:73], v[88:89] op_sel_hi:[1,0]
	v_pk_mul_f32 v[74:75], v[74:75], v[88:89] op_sel_hi:[1,0]
	v_pk_mul_f32 v[84:85], v[84:85], v[88:89] op_sel_hi:[1,0]
	v_pk_mul_f32 v[86:87], v[86:87], v[88:89] op_sel_hi:[1,0]
	v_pk_fma_f32 v[56:57], v[24:25], v[56:57], v[28:29]
	v_pk_fma_f32 v[58:59], v[26:27], v[58:59], v[30:31]
	v_pk_fma_f32 v[60:61], v[16:17], v[60:61], v[20:21]
	v_pk_fma_f32 v[62:63], v[18:19], v[62:63], v[22:23]
	v_pk_fma_f32 v[72:73], v[8:9], v[72:73], v[12:13]
	v_pk_fma_f32 v[74:75], v[10:11], v[74:75], v[14:15]
	v_pk_fma_f32 v[84:85], v[0:1], v[84:85], v[4:5]
	v_pk_fma_f32 v[86:87], v[2:3], v[86:87], v[6:7]
	v_cvt_pk_bf16_f32 v56, v56, v57
	v_cvt_pk_bf16_f32 v57, v58, v59
	v_cvt_pk_bf16_f32 v58, v60, v61
	v_cvt_pk_bf16_f32 v59, v62, v63
	v_cvt_pk_bf16_f32 v60, v72, v73
	v_cvt_pk_bf16_f32 v61, v74, v75
	v_cvt_pk_bf16_f32 v62, v84, v85
	v_cvt_pk_bf16_f32 v63, v86, v87
	global_store_dwordx4 v[70:71], v[56:59], off
	global_store_dwordx4 v[70:71], v[60:63], off offset:16
	s_branch .LBB0_758
